# ssm pass-3 y-section: removed the 8 now-dead 64-bit X-address computations per half-chunk (liveness checked per site)
# speedup vs baseline: 1.0010x; 1.0010x over previous
; #define LAS __attribute__((address_space(3)))
; __device__ __forceinline__ unsigned pk2(float lo, float hi) { const f32x2 v = {lo, hi}; const bf16x2_t b = __builtin_convertvector(v, bf16x2_t); return __builtin_bit_cast(unsigned, b); }
; #define CBAR() asm volatile("s_waitcnt lgkmcnt(0)" ::: "memory")
; template <int PASS> __device__ __forceinline__ void ssm_phase(int j, LAS unsigned char* lds, int lane, int wave) { KARGS;
;     ...
;                 for (int lt = 0; lt < 2; ++lt) {
;                     bf16x8 uf = {0, 0, 0, 0, 0, 0, 0, 0};
;                     if (fq < 2) { const int l = 32 * half + 16 * lt + fr; const float rs = rsL[l]; const float* xp = X + (size_t)(64 * c + l) * D + 16 * g + 8 * fq;
;                         const f32x4 x0 = *(const f32x4*)xp * rs, x1 = *(const f32x4*)(xp + 4) * rs;
;                         u32x4 w; w.x = pk2(x0[0], x0[1]); w.y = pk2(x0[2], x0[3]); w.z = pk2(x1[0], x1[1]); w.w = pk2(x1[2], x1[3]); uf = __builtin_bit_cast(bf16x8, w); }
;                     f32x4 dre[4], dim[4];
; #pragma unroll
;                     for (int pt = 0; pt < 4; ++pt) { const f32x4 z4 = {0.f, 0.f, 0.f, 0.f};
;                         dre[pt] = __builtin_amdgcn_mfma_f32_16x16x32_bf16(uf, bfr[pt], z4, 0, 0, 0); dim[pt] = __builtin_amdgcn_mfma_f32_16x16x32_bf16(uf, bfi[pt], z4, 0, 0, 0); }
;                     asm volatile("s_nop 15\n\ts_nop 15" : "+v"(dre[0]), "+v"(dre[1]), "+v"(dre[2]), "+v"(dre[3]), "+v"(dim[0]), "+v"(dim[1]), "+v"(dim[2]), "+v"(dim[3]));
; #pragma unroll
;                     for (int pt = 0; pt < 4; ++pt)
; #pragma unroll
;                         for (int r = 0; r < 4; ++r) *(LAS unsigned*)(buL + (16 * lt + 4 * fq + r) * 256 + 4 * (16 * pt + fr)) = pk2(dre[pt][r], dim[pt][r]);
;                 }
;                 CBAR();
; #pragma unroll 1
;                 for (int l8 = 0; l8 < 32; l8 += 8) {
;                     unsigned w[8];
; #pragma unroll
;                     for (int q = 0; q < 8; ++q) w[q] = *(const LAS unsigned*)(buL + (l8 + q) * 256 + 4 * p);
; #pragma unroll
;                     for (int q = 0; q < 8; ++q) {
;                         const float nr = abr * hr - abi * hi + bflo(w[q]), ni = abr * hi + abi * hr + bfhi(w[q]); hr = nr; hi = ni;
;                         if (PASS == 3) *(LAS unsigned*)(hL + (l8 + q) * 256 + ((((p >> 2) ^ ((l8 + q) & 15))) << 4) + (p & 3) * 4) = pk2(hr, hi);
.LBB0_347:
	s_or_b64 exec, exec, s[10:11]
	s_nop 0
	v_mfma_f32_16x16x32_bf16 v[56:59], v[52:55], v[12:15], 0
	s_xor_b64 s[10:11], s[4:5], -1
	s_mov_b32 s4, -8
	v_mfma_f32_16x16x32_bf16 v[98:101], v[52:55], v[8:11], 0
	v_mfma_f32_16x16x32_bf16 v[102:105], v[52:55], v[16:19], 0
	v_mfma_f32_16x16x32_bf16 v[106:109], v[52:55], v[4:7], 0
	v_mfma_f32_16x16x32_bf16 v[110:113], v[52:55], v[28:31], 0
	v_mfma_f32_16x16x32_bf16 v[114:117], v[52:55], v[24:27], 0
	v_mfma_f32_16x16x32_bf16 v[118:121], v[52:55], v[32:35], 0
	v_mfma_f32_16x16x32_bf16 v[52:55], v[52:55], v[20:23], 0
	s_nop 15
	s_nop 15
	s_nop 1
	v_cvt_pk_bf16_f32 v56, v56, v98
	s_nop 0
	v_cvt_pk_bf16_f32 v97, v102, v106
	v_add_u32_e32 v98, 0x3000, v96
	v_cvt_pk_bf16_f32 v57, v57, v99
	ds_write2_b32 v98, v56, v97 offset1:16
	v_cvt_pk_bf16_f32 v56, v103, v107
	v_cvt_pk_bf16_f32 v58, v58, v100
	ds_write2_b32 v98, v57, v56 offset0:64 offset1:80
	v_cvt_pk_bf16_f32 v56, v104, v108
	v_cvt_pk_bf16_f32 v59, v59, v101
	ds_write2_b32 v98, v58, v56 offset0:128 offset1:144
	v_cvt_pk_bf16_f32 v56, v105, v109
	ds_write2_b32 v98, v59, v56 offset0:192 offset1:208
	v_cvt_pk_bf16_f32 v56, v110, v114
	v_cvt_pk_bf16_f32 v52, v118, v52
	v_cvt_pk_bf16_f32 v57, v111, v115
	ds_write2_b32 v98, v56, v52 offset0:32 offset1:48
	v_cvt_pk_bf16_f32 v52, v119, v53
	v_cvt_pk_bf16_f32 v58, v112, v116
	ds_write2_b32 v98, v57, v52 offset0:96 offset1:112
	v_cvt_pk_bf16_f32 v52, v120, v54
	v_cvt_pk_bf16_f32 v59, v113, v117
	ds_write2_b32 v98, v58, v52 offset0:160 offset1:176
	v_cvt_pk_bf16_f32 v52, v121, v55
	ds_write2_b32 v98, v59, v52 offset0:224 offset1:240
	s_waitcnt lgkmcnt(0)
	ds_read2st64_b32 v[52:53], v211 offset0:0 offset1:1
	ds_read2st64_b32 v[54:55], v211 offset0:2 offset1:3
	ds_read2st64_b32 v[56:57], v211 offset0:4 offset1:5
	ds_read2st64_b32 v[58:59], v211 offset0:6 offset1:7
	s_waitcnt lgkmcnt(0)
	ds_read2st64_b32 v[98:99], v211 offset0:8 offset1:9
	ds_read2st64_b32 v[100:101], v211 offset0:10 offset1:11
	ds_read2st64_b32 v[102:103], v211 offset0:12 offset1:13
	ds_read2st64_b32 v[104:105], v211 offset0:14 offset1:15
	v_mul_f32_e32 v106, v84, v0
	v_mul_f32_e32 v107, v85, v1
	v_lshlrev_b32_e32 v108, 16, v52
	v_and_b32_e32 v109, 0xffff0000, v52
	v_fma_f32 v0, v2, v0, -v107
	v_fma_f32 v1, v3, v1, v106
	v_add_f32_e32 v0, v0, v108
	v_add_f32_e32 v1, v1, v109
	v_cvt_pk_bf16_f32 v110, v0, v1
	ds_write_b32 v195, v110
	v_mul_f32_e32 v111, v84, v0
	v_mul_f32_e32 v112, v85, v1
	v_lshlrev_b32_e32 v113, 16, v53
	v_and_b32_e32 v114, 0xffff0000, v53
	v_fma_f32 v0, v2, v0, -v112
	v_fma_f32 v1, v3, v1, v111
	v_add_f32_e32 v0, v0, v113
	v_add_f32_e32 v1, v1, v114
	v_cvt_pk_bf16_f32 v115, v0, v1
	ds_write_b32 v196, v115 offset:256
	v_mul_f32_e32 v106, v84, v0
	v_mul_f32_e32 v107, v85, v1
	v_lshlrev_b32_e32 v108, 16, v54
	v_and_b32_e32 v109, 0xffff0000, v54
	v_fma_f32 v0, v2, v0, -v107
	v_fma_f32 v1, v3, v1, v106
	v_add_f32_e32 v0, v0, v108
	v_add_f32_e32 v1, v1, v109
	v_cvt_pk_bf16_f32 v110, v0, v1
	ds_write_b32 v197, v110 offset:512
	v_mul_f32_e32 v111, v84, v0
	v_mul_f32_e32 v112, v85, v1
	v_lshlrev_b32_e32 v113, 16, v55
	v_and_b32_e32 v114, 0xffff0000, v55
	v_fma_f32 v0, v2, v0, -v112
	v_fma_f32 v1, v3, v1, v111
	v_add_f32_e32 v0, v0, v113
	v_add_f32_e32 v1, v1, v114
	v_cvt_pk_bf16_f32 v115, v0, v1
	ds_write_b32 v198, v115 offset:768
	v_mul_f32_e32 v106, v84, v0
	v_mul_f32_e32 v107, v85, v1
	v_lshlrev_b32_e32 v108, 16, v56
	v_and_b32_e32 v109, 0xffff0000, v56
	v_fma_f32 v0, v2, v0, -v107
	v_fma_f32 v1, v3, v1, v106
	v_add_f32_e32 v0, v0, v108
	v_add_f32_e32 v1, v1, v109
	v_cvt_pk_bf16_f32 v110, v0, v1
	ds_write_b32 v199, v110 offset:1024
	v_mul_f32_e32 v111, v84, v0
	v_mul_f32_e32 v112, v85, v1
	v_lshlrev_b32_e32 v113, 16, v57
	v_and_b32_e32 v114, 0xffff0000, v57
	v_fma_f32 v0, v2, v0, -v112
	v_fma_f32 v1, v3, v1, v111
	v_add_f32_e32 v0, v0, v113
	v_add_f32_e32 v1, v1, v114
	v_cvt_pk_bf16_f32 v115, v0, v1
	ds_write_b32 v200, v115 offset:1280
	v_mul_f32_e32 v106, v84, v0
	v_mul_f32_e32 v107, v85, v1
	v_lshlrev_b32_e32 v108, 16, v58
	v_and_b32_e32 v109, 0xffff0000, v58
	v_fma_f32 v0, v2, v0, -v107
	v_fma_f32 v1, v3, v1, v106
	v_add_f32_e32 v0, v0, v108
	v_add_f32_e32 v1, v1, v109
	v_cvt_pk_bf16_f32 v110, v0, v1
	ds_write_b32 v201, v110 offset:1536
	v_mul_f32_e32 v111, v84, v0
	v_mul_f32_e32 v112, v85, v1
	v_lshlrev_b32_e32 v113, 16, v59
	v_and_b32_e32 v114, 0xffff0000, v59
	v_fma_f32 v0, v2, v0, -v112
	v_fma_f32 v1, v3, v1, v111
	v_add_f32_e32 v0, v0, v113
	v_add_f32_e32 v1, v1, v114
	v_cvt_pk_bf16_f32 v115, v0, v1
	ds_write_b32 v202, v115 offset:1792
	s_waitcnt lgkmcnt(8)
; #define LAS __attribute__((address_space(3)))
; __device__ __forceinline__ unsigned pk2(float lo, float hi) { const f32x2 v = {lo, hi}; const bf16x2_t b = __builtin_convertvector(v, bf16x2_t); return __builtin_bit_cast(unsigned, b); }
; template <int PASS> __device__ __forceinline__ void ssm_phase(int j, LAS unsigned char* lds, int lane, int wave) { KARGS;
;     ...
;                 for (int l8 = 0; l8 < 32; l8 += 8) {
;                     unsigned w[8];
; #pragma unroll
;                     for (int q = 0; q < 8; ++q) w[q] = *(const LAS unsigned*)(buL + (l8 + q) * 256 + 4 * p);
; #pragma unroll
;                     for (int q = 0; q < 8; ++q) {
;                         const float nr = abr * hr - abi * hi + bflo(w[q]), ni = abr * hi + abi * hr + bfhi(w[q]); hr = nr; hi = ni;
;                         if (PASS == 3) *(LAS unsigned*)(hL + (l8 + q) * 256 + ((((p >> 2) ^ ((l8 + q) & 15))) << 4) + (p & 3) * 4) = pk2(hr, hi);
;                     }
	ds_read2st64_b32 v[52:53], v211 offset0:16 offset1:17
	ds_read2st64_b32 v[54:55], v211 offset0:18 offset1:19
	ds_read2st64_b32 v[56:57], v211 offset0:20 offset1:21
	ds_read2st64_b32 v[58:59], v211 offset0:22 offset1:23
	v_mul_f32_e32 v106, v84, v0
	v_mul_f32_e32 v107, v85, v1
	v_lshlrev_b32_e32 v108, 16, v98
	v_and_b32_e32 v109, 0xffff0000, v98
	v_fma_f32 v0, v2, v0, -v107
	v_fma_f32 v1, v3, v1, v106
	v_add_f32_e32 v0, v0, v108
	v_add_f32_e32 v1, v1, v109
	v_cvt_pk_bf16_f32 v110, v0, v1
	ds_write_b32 v203, v110 offset:2048
	v_mul_f32_e32 v111, v84, v0
	v_mul_f32_e32 v112, v85, v1
	v_lshlrev_b32_e32 v113, 16, v99
	v_and_b32_e32 v114, 0xffff0000, v99
	v_fma_f32 v0, v2, v0, -v112
	v_fma_f32 v1, v3, v1, v111
	v_add_f32_e32 v0, v0, v113
	v_add_f32_e32 v1, v1, v114
	v_cvt_pk_bf16_f32 v115, v0, v1
	ds_write_b32 v204, v115 offset:2304
	v_mul_f32_e32 v106, v84, v0
	v_mul_f32_e32 v107, v85, v1
	v_lshlrev_b32_e32 v108, 16, v100
	v_and_b32_e32 v109, 0xffff0000, v100
	v_fma_f32 v0, v2, v0, -v107
	v_fma_f32 v1, v3, v1, v106
	v_add_f32_e32 v0, v0, v108
	v_add_f32_e32 v1, v1, v109
	v_cvt_pk_bf16_f32 v110, v0, v1
	ds_write_b32 v205, v110 offset:2560
	v_mul_f32_e32 v111, v84, v0
	v_mul_f32_e32 v112, v85, v1
	v_lshlrev_b32_e32 v113, 16, v101
	v_and_b32_e32 v114, 0xffff0000, v101
	v_fma_f32 v0, v2, v0, -v112
	v_fma_f32 v1, v3, v1, v111
	v_add_f32_e32 v0, v0, v113
	v_add_f32_e32 v1, v1, v114
	v_cvt_pk_bf16_f32 v115, v0, v1
	ds_write_b32 v206, v115 offset:2816
	v_mul_f32_e32 v106, v84, v0
	v_mul_f32_e32 v107, v85, v1
	v_lshlrev_b32_e32 v108, 16, v102
	v_and_b32_e32 v109, 0xffff0000, v102
	v_fma_f32 v0, v2, v0, -v107
	v_fma_f32 v1, v3, v1, v106
	v_add_f32_e32 v0, v0, v108
	v_add_f32_e32 v1, v1, v109
	v_cvt_pk_bf16_f32 v110, v0, v1
	ds_write_b32 v207, v110 offset:3072
	v_mul_f32_e32 v111, v84, v0
	v_mul_f32_e32 v112, v85, v1
	v_lshlrev_b32_e32 v113, 16, v103
	v_and_b32_e32 v114, 0xffff0000, v103
	v_fma_f32 v0, v2, v0, -v112
	v_fma_f32 v1, v3, v1, v111
	v_add_f32_e32 v0, v0, v113
	v_add_f32_e32 v1, v1, v114
	v_cvt_pk_bf16_f32 v115, v0, v1
	ds_write_b32 v208, v115 offset:3328
	v_mul_f32_e32 v106, v84, v0
	v_mul_f32_e32 v107, v85, v1
	v_lshlrev_b32_e32 v108, 16, v104
	v_and_b32_e32 v109, 0xffff0000, v104
	v_fma_f32 v0, v2, v0, -v107
	v_fma_f32 v1, v3, v1, v106
	v_add_f32_e32 v0, v0, v108
	v_add_f32_e32 v1, v1, v109
	v_cvt_pk_bf16_f32 v110, v0, v1
	ds_write_b32 v209, v110 offset:3584
	v_mul_f32_e32 v111, v84, v0
	v_mul_f32_e32 v112, v85, v1
	v_lshlrev_b32_e32 v113, 16, v105
	v_and_b32_e32 v114, 0xffff0000, v105
	v_fma_f32 v0, v2, v0, -v112
	v_fma_f32 v1, v3, v1, v111
	v_add_f32_e32 v0, v0, v113
	v_add_f32_e32 v1, v1, v114
	v_cvt_pk_bf16_f32 v115, v0, v1
	ds_write_b32 v210, v115 offset:3840
	s_waitcnt lgkmcnt(8)
	ds_read2st64_b32 v[98:99], v211 offset0:24 offset1:25
	ds_read2st64_b32 v[100:101], v211 offset0:26 offset1:27
	ds_read2st64_b32 v[102:103], v211 offset0:28 offset1:29
	ds_read2st64_b32 v[104:105], v211 offset0:30 offset1:31
	v_mul_f32_e32 v106, v84, v0
	v_mul_f32_e32 v107, v85, v1
	v_lshlrev_b32_e32 v108, 16, v52
	v_and_b32_e32 v109, 0xffff0000, v52
	v_fma_f32 v0, v2, v0, -v107
	v_fma_f32 v1, v3, v1, v106
	v_add_f32_e32 v0, v0, v108
	v_add_f32_e32 v1, v1, v109
	v_cvt_pk_bf16_f32 v110, v0, v1
	ds_write_b32 v195, v110 offset:4096
	v_mul_f32_e32 v111, v84, v0
	v_mul_f32_e32 v112, v85, v1
	v_lshlrev_b32_e32 v113, 16, v53
	v_and_b32_e32 v114, 0xffff0000, v53
	v_fma_f32 v0, v2, v0, -v112
	v_fma_f32 v1, v3, v1, v111
	v_add_f32_e32 v0, v0, v113
	v_add_f32_e32 v1, v1, v114
	v_cvt_pk_bf16_f32 v115, v0, v1
	ds_write_b32 v196, v115 offset:4352
	v_mul_f32_e32 v106, v84, v0
	v_mul_f32_e32 v107, v85, v1
	v_lshlrev_b32_e32 v108, 16, v54
	v_and_b32_e32 v109, 0xffff0000, v54
	v_fma_f32 v0, v2, v0, -v107
	v_fma_f32 v1, v3, v1, v106
	v_add_f32_e32 v0, v0, v108
	v_add_f32_e32 v1, v1, v109
	v_cvt_pk_bf16_f32 v110, v0, v1
	ds_write_b32 v197, v110 offset:4608
	v_mul_f32_e32 v111, v84, v0
	v_mul_f32_e32 v112, v85, v1
	v_lshlrev_b32_e32 v113, 16, v55
	v_and_b32_e32 v114, 0xffff0000, v55
	v_fma_f32 v0, v2, v0, -v112
	v_fma_f32 v1, v3, v1, v111
	v_add_f32_e32 v0, v0, v113
	v_add_f32_e32 v1, v1, v114
	v_cvt_pk_bf16_f32 v115, v0, v1
	ds_write_b32 v198, v115 offset:4864
	v_mul_f32_e32 v106, v84, v0
	v_mul_f32_e32 v107, v85, v1
	v_lshlrev_b32_e32 v108, 16, v56
	v_and_b32_e32 v109, 0xffff0000, v56
	v_fma_f32 v0, v2, v0, -v107
	v_fma_f32 v1, v3, v1, v106
	v_add_f32_e32 v0, v0, v108
	v_add_f32_e32 v1, v1, v109
	v_cvt_pk_bf16_f32 v110, v0, v1
	ds_write_b32 v199, v110 offset:5120
	v_mul_f32_e32 v111, v84, v0
	v_mul_f32_e32 v112, v85, v1
	v_lshlrev_b32_e32 v113, 16, v57
	v_and_b32_e32 v114, 0xffff0000, v57
	v_fma_f32 v0, v2, v0, -v112
	v_fma_f32 v1, v3, v1, v111
	v_add_f32_e32 v0, v0, v113
	v_add_f32_e32 v1, v1, v114
	v_cvt_pk_bf16_f32 v115, v0, v1
	ds_write_b32 v200, v115 offset:5376
	v_mul_f32_e32 v106, v84, v0
	v_mul_f32_e32 v107, v85, v1
	v_lshlrev_b32_e32 v108, 16, v58
	v_and_b32_e32 v109, 0xffff0000, v58
	v_fma_f32 v0, v2, v0, -v107
	v_fma_f32 v1, v3, v1, v106
	v_add_f32_e32 v0, v0, v108
	v_add_f32_e32 v1, v1, v109
	v_cvt_pk_bf16_f32 v110, v0, v1
	ds_write_b32 v201, v110 offset:5632
	v_mul_f32_e32 v111, v84, v0
	v_mul_f32_e32 v112, v85, v1
	v_lshlrev_b32_e32 v113, 16, v59
	v_and_b32_e32 v114, 0xffff0000, v59
	v_fma_f32 v0, v2, v0, -v112
	v_fma_f32 v1, v3, v1, v111
	v_add_f32_e32 v0, v0, v113
	v_add_f32_e32 v1, v1, v114
	v_cvt_pk_bf16_f32 v115, v0, v1
	ds_write_b32 v202, v115 offset:5888
	s_waitcnt lgkmcnt(8)
; #define LAS __attribute__((address_space(3)))
; __device__ __forceinline__ unsigned f2bf(float f) { unsigned u = __builtin_bit_cast(unsigned, f); return (u + 0x7fffu + ((u >> 16) & 1u)) >> 16; }
; __device__ __forceinline__ float gelu_tanh(float v) { const float z = 0.7978845608028654f * (v + 0.044715f * v * v * v); return v * (1.0f - 1.0f / (1.0f + __expf(2.0f * z))); }
; template <int PASS> __device__ __forceinline__ void ssm_phase(int j, LAS unsigned char* lds, int lane, int wave) { KARGS;
;     ...
;                 if (PASS == 3) {
; #pragma unroll
;                     for (int lt = 0; lt < 2; ++lt) {
;                         f32x4 y = {0.f, 0.f, 0.f, 0.f};
; #pragma unroll
;                         for (int ks = 0; ks < 4; ++ks) { const bf16x8 hf = *(const LAS bf16x8*)(hL + (16 * lt + fr) * 256 + (((4 * ks + fq) ^ fr) << 4)); y = __builtin_amdgcn_mfma_f32_16x16x32_bf16(hf, cf[ks], y, 0, 0, 0); }
;                         asm volatile("s_nop 15\n\ts_nop 15" : "+v"(y));
;                         const int ch = 16 * g + fr;
; #pragma unroll
;                         for (int r = 0; r < 4; ++r) { const int l = 32 * half + 16 * lt + 4 * fq + r; const size_t t = (size_t)(64 * c + l);
;                             const float v = y[r] + dd * X[t * D + ch] * rsL[l];
;                             GL[t * D + ch] = (bf16_t)f2bf(gelu_tanh(v)); }
	v_mul_f32_e32 v106, v84, v0
	v_mul_f32_e32 v107, v85, v1
	v_lshlrev_b32_e32 v108, 16, v98
	v_and_b32_e32 v109, 0xffff0000, v98
	v_fma_f32 v0, v2, v0, -v107
	v_fma_f32 v1, v3, v1, v106
	v_add_f32_e32 v0, v0, v108
	v_add_f32_e32 v1, v1, v109
	v_cvt_pk_bf16_f32 v110, v0, v1
	ds_write_b32 v203, v110 offset:6144
	v_mul_f32_e32 v111, v84, v0
	v_mul_f32_e32 v112, v85, v1
	v_lshlrev_b32_e32 v113, 16, v99
	v_and_b32_e32 v114, 0xffff0000, v99
	v_fma_f32 v0, v2, v0, -v112
	v_fma_f32 v1, v3, v1, v111
	v_add_f32_e32 v0, v0, v113
	v_add_f32_e32 v1, v1, v114
	v_cvt_pk_bf16_f32 v115, v0, v1
	ds_write_b32 v204, v115 offset:6400
	v_mul_f32_e32 v106, v84, v0
	v_mul_f32_e32 v107, v85, v1
	v_lshlrev_b32_e32 v108, 16, v100
	v_and_b32_e32 v109, 0xffff0000, v100
	v_fma_f32 v0, v2, v0, -v107
	v_fma_f32 v1, v3, v1, v106
	v_add_f32_e32 v0, v0, v108
	v_add_f32_e32 v1, v1, v109
	v_cvt_pk_bf16_f32 v110, v0, v1
	ds_write_b32 v205, v110 offset:6656
	v_mul_f32_e32 v111, v84, v0
	v_mul_f32_e32 v112, v85, v1
	v_lshlrev_b32_e32 v113, 16, v101
	v_and_b32_e32 v114, 0xffff0000, v101
	v_fma_f32 v0, v2, v0, -v112
	v_fma_f32 v1, v3, v1, v111
	v_add_f32_e32 v0, v0, v113
	v_add_f32_e32 v1, v1, v114
	v_cvt_pk_bf16_f32 v115, v0, v1
	ds_write_b32 v206, v115 offset:6912
	v_mul_f32_e32 v106, v84, v0
	v_mul_f32_e32 v107, v85, v1
	v_lshlrev_b32_e32 v108, 16, v102
	v_and_b32_e32 v109, 0xffff0000, v102
	v_fma_f32 v0, v2, v0, -v107
	v_fma_f32 v1, v3, v1, v106
	v_add_f32_e32 v0, v0, v108
	v_add_f32_e32 v1, v1, v109
	v_cvt_pk_bf16_f32 v110, v0, v1
	ds_write_b32 v207, v110 offset:7168
	v_mul_f32_e32 v111, v84, v0
	v_mul_f32_e32 v112, v85, v1
	v_lshlrev_b32_e32 v113, 16, v103
	v_and_b32_e32 v114, 0xffff0000, v103
	v_fma_f32 v0, v2, v0, -v112
	v_fma_f32 v1, v3, v1, v111
	v_add_f32_e32 v0, v0, v113
	v_add_f32_e32 v1, v1, v114
	v_cvt_pk_bf16_f32 v115, v0, v1
	ds_write_b32 v208, v115 offset:7424
	v_mul_f32_e32 v106, v84, v0
	v_mul_f32_e32 v107, v85, v1
	v_lshlrev_b32_e32 v108, 16, v104
	v_and_b32_e32 v109, 0xffff0000, v104
	v_fma_f32 v0, v2, v0, -v107
	v_fma_f32 v1, v3, v1, v106
	v_add_f32_e32 v0, v0, v108
	v_add_f32_e32 v1, v1, v109
	v_cvt_pk_bf16_f32 v110, v0, v1
	ds_write_b32 v209, v110 offset:7680
	v_mul_f32_e32 v111, v84, v0
	v_mul_f32_e32 v112, v85, v1
	v_lshlrev_b32_e32 v113, 16, v105
	v_and_b32_e32 v114, 0xffff0000, v105
	v_fma_f32 v0, v2, v0, -v112
	v_fma_f32 v1, v3, v1, v111
	v_add_f32_e32 v0, v0, v113
	v_add_f32_e32 v1, v1, v114
	v_cvt_pk_bf16_f32 v115, v0, v1
	ds_write_b32 v210, v115 offset:7936
	s_waitcnt lgkmcnt(0)
	ds_read_b128 v[52:55], v87
	ds_read_b128 v[56:59], v92
	v_or_b32_e32 v97, s70, v72
	v_lshl_add_u32 v98, v97, 2, s18
	s_mov_b32 s70, 32
	s_waitcnt lgkmcnt(1)
	v_mfma_f32_16x16x32_bf16 v[52:55], v[52:55], v[36:39], 0
	s_waitcnt lgkmcnt(0)
	v_mfma_f32_16x16x32_bf16 v[52:55], v[56:59], v[40:43], v[52:55]
	ds_read_b128 v[56:59], v93
	s_waitcnt lgkmcnt(0)
	v_mfma_f32_16x16x32_bf16 v[52:55], v[56:59], v[44:47], v[52:55]
	ds_read_b128 v[56:59], v94
	s_waitcnt lgkmcnt(0)
	v_mfma_f32_16x16x32_bf16 v[52:55], v[56:59], v[48:51], v[52:55]
	v_or_b32_e32 v56, s12, v97
	v_ashrrev_i32_e32 v57, 31, v56
	v_lshlrev_b64 v[100:101], 11, v[56:57]
	v_or_b32_e32 v100, v100, v86
	s_nop 15
	s_nop 15
	v_lshlrev_b32_e32 v246, 1, v100
	v_lshl_add_u64 v[100:101], v[100:101], 1, s[64:65]
	v_mul_f32_e32 v99, v83, v126
	ds_read_b128 v[56:59], v98 offset:16384
	s_waitcnt lgkmcnt(0)
	v_fma_f32 v52, v99, v56, v52
	v_mul_f32_e32 v56, 0x3d372713, v52
	v_mul_f32_e32 v56, v52, v56
	v_fma_f32 v56, v52, v56, v52
	v_mul_f32_e32 v56, 0x3f4c422a, v56
	v_add_f32_e32 v56, v56, v56
	v_mul_f32_e32 v56, 0x3fb8aa3b, v56
	v_exp_f32_e32 v56, v56
	s_nop 0
	v_add_f32_e32 v56, 1.0, v56
	v_div_scale_f32 v99, s[4:5], v56, v56, 1.0
	v_rcp_f32_e32 v102, v99
	s_nop 0
	v_fma_f32 v103, -v99, v102, 1.0
	v_fmac_f32_e32 v102, v103, v102
	v_div_scale_f32 v103, vcc, 1.0, v56, 1.0
	v_mul_f32_e32 v104, v103, v102
	v_fma_f32 v105, -v99, v104, v103
	v_fmac_f32_e32 v104, v105, v102
	v_fma_f32 v99, -v99, v104, v103
	v_div_fmas_f32 v99, v99, v102, v104
	v_div_fixup_f32 v56, v99, v56, 1.0
	v_sub_f32_e32 v56, 1.0, v56
	v_mul_f32_e32 v52, v52, v56
	v_bfe_u32 v56, v52, 16, 1
	v_add3_u32 v52, v52, v56, s75
	v_mov_b32_e32 v212, v52
	v_or_b32_e32 v100, s54, v97
	v_ashrrev_i32_e32 v101, 31, v100
	v_lshlrev_b64 v[100:101], 11, v[100:101]
	v_or_b32_e32 v100, v100, v86
	v_mul_f32_e32 v52, v83, v127
	v_fma_f32 v52, v52, v57, v53
	v_mul_f32_e32 v53, 0x3d372713, v52
	v_mul_f32_e32 v53, v52, v53
	v_fma_f32 v53, v52, v53, v52
	v_mul_f32_e32 v53, 0x3f4c422a, v53
	v_add_f32_e32 v53, v53, v53
	v_mul_f32_e32 v53, 0x3fb8aa3b, v53
	v_exp_f32_e32 v53, v53
	s_nop 0
	v_add_f32_e32 v53, 1.0, v53
	v_div_scale_f32 v56, s[4:5], v53, v53, 1.0
	v_rcp_f32_e32 v57, v56
	s_nop 0
	v_fma_f32 v99, -v56, v57, 1.0
	v_fmac_f32_e32 v57, v99, v57
	v_div_scale_f32 v99, vcc, 1.0, v53, 1.0
	v_mul_f32_e32 v102, v99, v57
	v_fma_f32 v103, -v56, v102, v99
	v_fmac_f32_e32 v102, v103, v57
	v_fma_f32 v56, -v56, v102, v99
	v_div_fmas_f32 v56, v56, v57, v102
	v_div_fixup_f32 v53, v56, v53, 1.0
	v_sub_f32_e32 v53, 1.0, v53
	v_mul_f32_e32 v52, v52, v53
	v_bfe_u32 v53, v52, 16, 1
	v_add3_u32 v56, v52, v53, s75
	v_lshlrev_b32_e32 v247, 1, v100
	v_lshl_add_u64 v[52:53], v[100:101], 1, s[64:65]
	v_mov_b32_e32 v213, v56
	v_or_b32_e32 v52, s55, v97
	v_ashrrev_i32_e32 v53, 31, v52
	v_lshlrev_b64 v[52:53], 11, v[52:53]
	v_or_b32_e32 v52, v52, v86
	v_lshlrev_b32_e32 v248, 1, v52
	v_lshl_add_u64 v[52:53], v[52:53], 1, s[64:65]
	v_mul_f32_e32 v56, v83, v128
	v_fma_f32 v54, v56, v58, v54
	v_mul_f32_e32 v56, 0x3d372713, v54
	v_mul_f32_e32 v56, v54, v56
	v_fma_f32 v56, v54, v56, v54
	v_mul_f32_e32 v56, 0x3f4c422a, v56
; #define LAS __attribute__((address_space(3)))
; __device__ __forceinline__ unsigned f2bf(float f) { unsigned u = __builtin_bit_cast(unsigned, f); return (u + 0x7fffu + ((u >> 16) & 1u)) >> 16; }
; __device__ __forceinline__ float gelu_tanh(float v) { const float z = 0.7978845608028654f * (v + 0.044715f * v * v * v); return v * (1.0f - 1.0f / (1.0f + __expf(2.0f * z))); }
; template <int PASS> __device__ __forceinline__ void ssm_phase(int j, LAS unsigned char* lds, int lane, int wave) { KARGS;
;     ...
;                 if (PASS == 3) {
; #pragma unroll
;                     for (int lt = 0; lt < 2; ++lt) {
;                         f32x4 y = {0.f, 0.f, 0.f, 0.f};
; #pragma unroll
;                         for (int ks = 0; ks < 4; ++ks) { const bf16x8 hf = *(const LAS bf16x8*)(hL + (16 * lt + fr) * 256 + (((4 * ks + fq) ^ fr) << 4)); y = __builtin_amdgcn_mfma_f32_16x16x32_bf16(hf, cf[ks], y, 0, 0, 0); }
;                         asm volatile("s_nop 15\n\ts_nop 15" : "+v"(y));
;                         const int ch = 16 * g + fr;
; #pragma unroll
;                         for (int r = 0; r < 4; ++r) { const int l = 32 * half + 16 * lt + 4 * fq + r; const size_t t = (size_t)(64 * c + l);
;                             const float v = y[r] + dd * X[t * D + ch] * rsL[l];
;                             GL[t * D + ch] = (bf16_t)f2bf(gelu_tanh(v)); }
	v_add_f32_e32 v56, v56, v56
	v_mul_f32_e32 v56, 0x3fb8aa3b, v56
	v_exp_f32_e32 v56, v56
	s_nop 0
	v_add_f32_e32 v56, 1.0, v56
	v_div_scale_f32 v57, s[4:5], v56, v56, 1.0
	v_rcp_f32_e32 v58, v57
	s_nop 0
	v_fma_f32 v99, -v57, v58, 1.0
	v_fmac_f32_e32 v58, v99, v58
	v_div_scale_f32 v99, vcc, 1.0, v56, 1.0
	v_mul_f32_e32 v100, v99, v58
	v_fma_f32 v101, -v57, v100, v99
	v_fmac_f32_e32 v100, v101, v58
	v_fma_f32 v57, -v57, v100, v99
	v_div_fmas_f32 v57, v57, v58, v100
	v_div_fixup_f32 v56, v57, v56, 1.0
	v_sub_f32_e32 v56, 1.0, v56
	v_mul_f32_e32 v54, v54, v56
	v_bfe_u32 v56, v54, 16, 1
	v_add3_u32 v54, v54, v56, s75
	v_mov_b32_e32 v214, v54
	v_or_b32_e32 v52, s68, v97
	v_ashrrev_i32_e32 v53, 31, v52
	v_lshlrev_b64 v[52:53], 11, v[52:53]
	v_or_b32_e32 v52, v52, v86
	v_lshlrev_b32_e32 v249, 1, v52
	v_lshl_add_u64 v[52:53], v[52:53], 1, s[64:65]
	v_mul_f32_e32 v54, v83, v129
	v_fmac_f32_e32 v55, v54, v59
	v_mul_f32_e32 v54, 0x3d372713, v55
	v_mul_f32_e32 v54, v55, v54
	v_fma_f32 v54, v55, v54, v55
	v_mul_f32_e32 v54, 0x3f4c422a, v54
	v_add_f32_e32 v54, v54, v54
	v_mul_f32_e32 v54, 0x3fb8aa3b, v54
	v_exp_f32_e32 v54, v54
	s_nop 0
	v_add_f32_e32 v54, 1.0, v54
	v_div_scale_f32 v56, s[4:5], v54, v54, 1.0
	v_rcp_f32_e32 v57, v56
	s_nop 0
	v_fma_f32 v58, -v56, v57, 1.0
	v_fmac_f32_e32 v57, v58, v57
	v_div_scale_f32 v58, vcc, 1.0, v54, 1.0
	v_mul_f32_e32 v59, v58, v57
	v_fma_f32 v99, -v56, v59, v58
	v_fmac_f32_e32 v59, v99, v57
	v_fma_f32 v56, -v56, v59, v58
	v_div_fmas_f32 v56, v56, v57, v59
	v_div_fixup_f32 v54, v56, v54, 1.0
	v_sub_f32_e32 v54, 1.0, v54
	v_mul_f32_e32 v54, v55, v54
	v_bfe_u32 v55, v54, 16, 1
	v_add3_u32 v54, v54, v55, s75
	v_mov_b32_e32 v215, v54
	ds_read_b128 v[52:55], v87 offset:4096
	ds_read_b128 v[56:59], v92 offset:4096
	s_waitcnt lgkmcnt(1)
	v_mfma_f32_16x16x32_bf16 v[52:55], v[52:55], v[36:39], 0
	s_waitcnt lgkmcnt(0)
	v_mfma_f32_16x16x32_bf16 v[52:55], v[56:59], v[40:43], v[52:55]
	ds_read_b128 v[56:59], v93 offset:4096
	s_waitcnt lgkmcnt(0)
	v_mfma_f32_16x16x32_bf16 v[52:55], v[56:59], v[44:47], v[52:55]
	ds_read_b128 v[56:59], v94 offset:4096
	s_waitcnt lgkmcnt(0)
	v_mfma_f32_16x16x32_bf16 v[52:55], v[56:59], v[48:51], v[52:55]
	v_or_b32_e32 v56, s13, v97
	v_ashrrev_i32_e32 v57, 31, v56
	v_lshlrev_b64 v[100:101], 11, v[56:57]
	v_or_b32_e32 v100, v100, v86
	s_nop 15
	s_nop 15
	v_mul_f32_e32 v99, v83, v130
	ds_read_b128 v[56:59], v98 offset:16448
	s_waitcnt lgkmcnt(0)
	v_fma_f32 v52, v99, v56, v52
	v_mul_f32_e32 v56, 0x3d372713, v52
	v_mul_f32_e32 v56, v52, v56
	v_fma_f32 v56, v52, v56, v52
	v_mul_f32_e32 v56, 0x3f4c422a, v56
	v_add_f32_e32 v56, v56, v56
	v_mul_f32_e32 v56, 0x3fb8aa3b, v56
	v_exp_f32_e32 v56, v56
	s_nop 0
	v_add_f32_e32 v56, 1.0, v56
	v_div_scale_f32 v98, s[4:5], v56, v56, 1.0
	v_rcp_f32_e32 v99, v98
	s_nop 0
	v_fma_f32 v102, -v98, v99, 1.0
	v_fmac_f32_e32 v99, v102, v99
	v_div_scale_f32 v102, vcc, 1.0, v56, 1.0
	v_mul_f32_e32 v103, v102, v99
	v_fma_f32 v104, -v98, v103, v102
	v_fmac_f32_e32 v103, v104, v99
	v_fma_f32 v98, -v98, v103, v102
	v_div_fmas_f32 v98, v98, v99, v103
	v_div_fixup_f32 v56, v98, v56, 1.0
	v_sub_f32_e32 v56, 1.0, v56
	v_mul_f32_e32 v52, v52, v56
	v_bfe_u32 v56, v52, 16, 1
	v_add3_u32 v52, v52, v56, s75
	v_lshlrev_b32_e32 v250, 1, v100
	v_lshl_add_u64 v[98:99], v[100:101], 1, s[64:65]
	v_mov_b32_e32 v216, v52
	v_or_b32_e32 v98, s77, v97
	v_ashrrev_i32_e32 v99, 31, v98
	v_lshlrev_b64 v[98:99], 11, v[98:99]
	v_or_b32_e32 v98, v98, v86
	v_mul_f32_e32 v52, v83, v131
	v_fma_f32 v52, v52, v57, v53
	v_mul_f32_e32 v53, 0x3d372713, v52
	v_mul_f32_e32 v53, v52, v53
	v_fma_f32 v53, v52, v53, v52
	v_mul_f32_e32 v53, 0x3f4c422a, v53
	v_add_f32_e32 v53, v53, v53
	v_mul_f32_e32 v53, 0x3fb8aa3b, v53
	v_exp_f32_e32 v53, v53
	s_nop 0
	v_add_f32_e32 v53, 1.0, v53
	v_div_scale_f32 v56, s[4:5], v53, v53, 1.0
	v_rcp_f32_e32 v57, v56
	s_nop 0
	v_fma_f32 v100, -v56, v57, 1.0
	v_fmac_f32_e32 v57, v100, v57
	v_div_scale_f32 v100, vcc, 1.0, v53, 1.0
	v_mul_f32_e32 v101, v100, v57
	v_fma_f32 v102, -v56, v101, v100
	v_fmac_f32_e32 v101, v102, v57
	v_fma_f32 v56, -v56, v101, v100
	v_div_fmas_f32 v56, v56, v57, v101
	v_div_fixup_f32 v53, v56, v53, 1.0
	v_sub_f32_e32 v53, 1.0, v53
	v_mul_f32_e32 v52, v52, v53
	v_bfe_u32 v53, v52, 16, 1
	v_add3_u32 v56, v52, v53, s75
	v_lshlrev_b32_e32 v251, 1, v98
	v_lshl_add_u64 v[52:53], v[98:99], 1, s[64:65]
	v_mov_b32_e32 v217, v56
	v_or_b32_e32 v52, s80, v97
	v_ashrrev_i32_e32 v53, 31, v52
	v_lshlrev_b64 v[52:53], 11, v[52:53]
	v_or_b32_e32 v52, v52, v86
	v_lshlrev_b32_e32 v252, 1, v52
	v_lshl_add_u64 v[52:53], v[52:53], 1, s[64:65]
	v_mul_f32_e32 v56, v83, v132
	v_fma_f32 v54, v56, v58, v54
	v_mul_f32_e32 v56, 0x3d372713, v54
	v_mul_f32_e32 v56, v54, v56
	v_fma_f32 v56, v54, v56, v54
	v_mul_f32_e32 v56, 0x3f4c422a, v56
	v_add_f32_e32 v56, v56, v56
	v_mul_f32_e32 v56, 0x3fb8aa3b, v56
	v_exp_f32_e32 v56, v56
	s_nop 0
	v_add_f32_e32 v56, 1.0, v56
	v_div_scale_f32 v57, s[4:5], v56, v56, 1.0
	v_rcp_f32_e32 v58, v57
	s_nop 0
	v_fma_f32 v98, -v57, v58, 1.0
	v_fmac_f32_e32 v58, v98, v58
	v_div_scale_f32 v98, vcc, 1.0, v56, 1.0
	v_mul_f32_e32 v99, v98, v58
	v_fma_f32 v100, -v57, v99, v98
	v_fmac_f32_e32 v99, v100, v58
	v_fma_f32 v57, -v57, v99, v98
	v_div_fmas_f32 v57, v57, v58, v99
	v_div_fixup_f32 v56, v57, v56, 1.0
	v_sub_f32_e32 v56, 1.0, v56
	v_mul_f32_e32 v54, v54, v56
	v_bfe_u32 v56, v54, 16, 1
	v_add3_u32 v54, v54, v56, s75
	v_mov_b32_e32 v244, v54
	v_or_b32_e32 v52, s81, v97
	v_ashrrev_i32_e32 v53, 31, v52
	v_lshlrev_b64 v[52:53], 11, v[52:53]
	v_or_b32_e32 v52, v52, v86
	v_lshlrev_b32_e32 v253, 1, v52
	v_lshl_add_u64 v[52:53], v[52:53], 1, s[64:65]
	v_mul_f32_e32 v54, v83, v133
	v_fmac_f32_e32 v55, v54, v59
	v_mul_f32_e32 v54, 0x3d372713, v55
	v_mul_f32_e32 v54, v55, v54
	v_fma_f32 v54, v55, v54, v55
	v_mul_f32_e32 v54, 0x3f4c422a, v54
	v_add_f32_e32 v54, v54, v54
	v_mul_f32_e32 v54, 0x3fb8aa3b, v54
	v_exp_f32_e32 v54, v54
	s_nop 0
	v_add_f32_e32 v54, 1.0, v54
	v_div_scale_f32 v56, s[4:5], v54, v54, 1.0
	v_rcp_f32_e32 v57, v56
	s_mov_b64 s[4:5], 0
	v_fma_f32 v58, -v56, v57, 1.0
	v_fmac_f32_e32 v57, v58, v57
	v_div_scale_f32 v58, vcc, 1.0, v54, 1.0
	v_mul_f32_e32 v59, v58, v57
	v_fma_f32 v97, -v56, v59, v58
	v_fmac_f32_e32 v59, v97, v57
	v_fma_f32 v56, -v56, v59, v58
	v_div_fmas_f32 v56, v56, v57, v59
	v_div_fixup_f32 v54, v56, v54, 1.0
	v_sub_f32_e32 v54, 1.0, v54
	v_mul_f32_e32 v54, v55, v54
	v_bfe_u32 v55, v54, 16, 1
	v_add3_u32 v54, v54, v55, s75
	v_mov_b32_e32 v245, v54
	s_waitcnt lgkmcnt(0)
	v_mov_b64_e32 v[126:127], v[236:237]
	v_mov_b64_e32 v[128:129], v[238:239]
	v_mov_b64_e32 v[130:131], v[240:241]
	v_mov_b64_e32 v[132:133], v[242:243]
	v_mov_b64_e32 v[156:157], v[172:173]
	v_mov_b64_e32 v[158:159], v[174:175]
	v_mov_b64_e32 v[160:161], v[176:177]
	v_mov_b64_e32 v[162:163], v[178:179]
	v_mov_b64_e32 v[164:165], v[180:181]
	v_mov_b64_e32 v[166:167], v[182:183]
	v_mov_b64_e32 v[168:169], v[184:185]
	v_mov_b64_e32 v[170:171], v[186:187]
	s_and_b64 vcc, exec, s[10:11]
	s_cbranch_vccnz .Lssm3_nofl
; __device__ __forceinline__ unsigned f2bf(float f) { unsigned u = __builtin_bit_cast(unsigned, f); return (u + 0x7fffu + ((u >> 16) & 1u)) >> 16; }
; __device__ __forceinline__ float gelu_tanh(float v) { const float z = 0.7978845608028654f * (v + 0.044715f * v * v * v); return v * (1.0f - 1.0f / (1.0f + __expf(2.0f * z))); }
; template <int PASS> __device__ __forceinline__ void ssm_phase(int j, LAS unsigned char* lds, int lane, int wave) { KARGS;
;     ...
;                             GL[t * D + ch] = (bf16_t)f2bf(gelu_tanh(v)); }
	global_store_short_d16_hi v246, v212, s[64:65]
	global_store_short_d16_hi v247, v213, s[64:65]
	global_store_short_d16_hi v248, v214, s[64:65]
	global_store_short_d16_hi v249, v215, s[64:65]
	global_store_short_d16_hi v250, v216, s[64:65]
	global_store_short_d16_hi v251, v217, s[64:65]
	global_store_short_d16_hi v252, v244, s[64:65]
	global_store_short_d16_hi v253, v245, s[64:65]
	s_branch .LBB0_343
